# attention tile loop edge: K/V global-load address increments hoisted above the tile barrier (off the post-barrier path)
# baseline (speedup 1.0000x reference)
; #define LAS __attribute__((address_space(3)))
; __device__ __forceinline__ void lds_barrier() { asm volatile("s_waitcnt lgkmcnt(0)" ::: "memory"); __builtin_amdgcn_s_barrier(); asm volatile("" ::: "memory"); }
; __device__ __forceinline__ u32x4 gload16_asm(const void* p) { u32x4 r; asm volatile("global_load_dwordx4 %0, %1, off" : "=v"(r) : "v"(p) : "memory"); return r; }
; __device__ __forceinline__ void attn_phase(const Args& a, LAS unsigned char* lds, const bf16* Qn, const bf16* Kn, const bf16* Vt, bf16* O, float* stash, int tid, int lane, int wave) {
;     ...
;                 if (t + 2 < NT) { kreg[hh] = gload16_asm(Kp + (size_t)(t + 2) * 4096); vreg0[hh] = gload16_asm(Vp + 64 * (t + 2)); vreg1[hh] = gload16_asm(Vp + (size_t)64 * SEQ + 64 * (t + 2)); }
;     ...
;                 if (t + 1 < NT) { if (t + 2 < NT) asm volatile("s_waitcnt vmcnt(3)" ::: "memory"); else asm volatile("s_waitcnt vmcnt(0)" ::: "memory");
;                     LAS unsigned char* d = lds + ((t + 1) & 1) * AT_BUF; *(LAS u32x4*)(d + kofs) = kreg[hh ^ 1]; *(LAS u32x4*)(d + AT_KB + kofs) = vreg0[hh ^ 1]; *(LAS u32x4*)(d + AT_KB + 64 * 144 + kofs) = vreg1[hh ^ 1]; }
;                 lds_barrier();
.LBB0_124:
	v_lshl_add_u64 v[190:191], v[190:191], 0, s[26:27]
	v_lshl_add_u64 v[188:189], v[188:189], 0, s[26:27]
	v_lshl_add_u64 v[192:193], v[192:193], 0, s[18:19]
	s_waitcnt lgkmcnt(0)
	s_barrier
	s_and_b64 vcc, exec, s[20:21]
	s_cbranch_vccnz .LBB0_132
	s_mov_b32 s2, s41
	s_branch .LBB0_106
